# statepass: store-data registers rotated over 4 tuples (safety); otherwise as previous
# speedup vs baseline: 1.0004x; 1.0004x over previous
; __device__ __forceinline__ float ozero() { float z = 0.f; asm volatile("" : "+v"(z)); return z; }
; __device__ __forceinline__ int otid() { return otid_full() & 255; }
; __device__ __forceinline__ void ssd_statepass(const Params& p, int task) {
;   const int idx = task * 256 + otid();
;   const int b = idx >> 15, e4 = idx & 32767;
;   const int hd = e4 >> 11;
;   const float zc_ = ozero(); float4 carry = make_float4(zc_, zc_, zc_, zc_);
;   float* base = p.ST + (size_t)b * 128 * 131072 + (size_t)e4 * 4;
;   const float* cd = p.CD + (size_t)b * 128 * 16 + hd;
;   for (int c0 = 0; c0 < 128; c0 += 4) {
;     float4 v[4]; float d[4];
; #pragma unroll
;     for (int k = 0; k < 4; k++) { v[k] = *(const float4*)(base + (size_t)(c0 + k) * 131072); d[k] = cd[(c0 + k) * 16]; }
; #pragma unroll
;     for (int k = 0; k < 4; k++) {
;       *(float4*)(base + (size_t)(c0 + k) * 131072) = carry;
;       carry.x = carry.x * d[k] + v[k].x; carry.y = carry.y * d[k] + v[k].y;
;       carry.z = carry.z * d[k] + v[k].z; carry.w = carry.w * d[k] + v[k].w;
;     }
;   }
.LBB0_536:
	s_andn2_b64 vcc, exec, s[0:1]
	s_cbranch_vccnz .LBB0_538
	s_and_b32 s1, s74, 0x80
	s_lshl_b32 s0, s74, 8
	s_and_b32 s0, s0, 0x7f00
	v_and_b32_e32 v0, 0xff, v203
	v_or_b32_e32 v0, s0, v0
	v_lshlrev_b32_e32 v144, 4, v0
	v_readlane_b32 s16, v253, 34
	v_readlane_b32 s17, v253, 35
	v_readlane_b32 s10, v253, 40
	v_readlane_b32 s11, v253, 41
	s_lshl_b32 s0, s1, 19
	s_nop 1
	s_add_u32 s4, s16, s0
	s_addc_u32 s5, s17, 0
	s_lshl_b32 s0, s1, 6
	s_add_u32 s2, s10, s0
	s_addc_u32 s3, s11, 0
	s_lshr_b32 s0, s74, 1
	s_and_b32 s6, s0, 60
	v_mbcnt_lo_u32_b32 v1, -1, 0
	v_mbcnt_hi_u32_b32 v1, -1, v1
	v_lshlrev_b32_e32 v2, 6, v1
	v_add_u32_e32 v2, s6, v2
	v_add_u32_e32 v3, 0x1000, v2
	global_load_dword v8, v2, s[2:3]
	global_load_dword v9, v3, s[2:3]
	v_mov_b32_e32 v4, 0
	v_mov_b32_e32 v5, 0
	v_mov_b32_e32 v6, 0
	v_mov_b32_e32 v7, 0
	global_load_dwordx4 v[16:19], v144, s[4:5]
	v_add_u32_e32 v14, 0x80000, v144
	global_load_dwordx4 v[20:23], v14, s[4:5]
	v_add_u32_e32 v15, 0x100000, v144
	global_load_dwordx4 v[24:27], v15, s[4:5]
	v_add_u32_e32 v14, 0x180000, v144
	global_load_dwordx4 v[28:31], v14, s[4:5]
	v_add_u32_e32 v15, 0x200000, v144
	global_load_dwordx4 v[32:35], v15, s[4:5]
	v_add_u32_e32 v14, 0x280000, v144
	global_load_dwordx4 v[36:39], v14, s[4:5]
	v_add_u32_e32 v15, 0x300000, v144
	global_load_dwordx4 v[40:43], v15, s[4:5]
	v_add_u32_e32 v14, 0x380000, v144
	global_load_dwordx4 v[44:47], v14, s[4:5]
	v_add_u32_e32 v15, 0x400000, v144
	global_load_dwordx4 v[48:51], v15, s[4:5]
	v_add_u32_e32 v14, 0x480000, v144
	global_load_dwordx4 v[52:55], v14, s[4:5]
	v_add_u32_e32 v15, 0x500000, v144
	global_load_dwordx4 v[56:59], v15, s[4:5]
	v_add_u32_e32 v14, 0x580000, v144
	global_load_dwordx4 v[60:63], v14, s[4:5]
	v_add_u32_e32 v15, 0x600000, v144
	global_load_dwordx4 v[64:67], v15, s[4:5]
	v_add_u32_e32 v14, 0x680000, v144
	global_load_dwordx4 v[68:71], v14, s[4:5]
	v_add_u32_e32 v15, 0x700000, v144
	global_load_dwordx4 v[72:75], v15, s[4:5]
	v_add_u32_e32 v14, 0x780000, v144
	global_load_dwordx4 v[76:79], v14, s[4:5]
	v_add_u32_e32 v15, 0x800000, v144
	global_load_dwordx4 v[80:83], v15, s[4:5]
	v_add_u32_e32 v14, 0x880000, v144
	global_load_dwordx4 v[84:87], v14, s[4:5]
	v_add_u32_e32 v15, 0x900000, v144
	global_load_dwordx4 v[88:91], v15, s[4:5]
	v_add_u32_e32 v14, 0x980000, v144
	global_load_dwordx4 v[92:95], v14, s[4:5]
	v_add_u32_e32 v15, 0xa00000, v144
	global_load_dwordx4 v[96:99], v15, s[4:5]
	v_add_u32_e32 v14, 0xa80000, v144
	global_load_dwordx4 v[100:103], v14, s[4:5]
	v_add_u32_e32 v15, 0xb00000, v144
	global_load_dwordx4 v[104:107], v15, s[4:5]
	v_add_u32_e32 v14, 0xb80000, v144
	global_load_dwordx4 v[108:111], v14, s[4:5]
	v_add_u32_e32 v15, 0xc00000, v144
	global_load_dwordx4 v[112:115], v15, s[4:5]
	v_add_u32_e32 v14, 0xc80000, v144
	global_load_dwordx4 v[116:119], v14, s[4:5]
	v_add_u32_e32 v15, 0xd00000, v144
	global_load_dwordx4 v[120:123], v15, s[4:5]
	v_add_u32_e32 v14, 0xd80000, v144
	global_load_dwordx4 v[124:127], v14, s[4:5]
	v_add_u32_e32 v15, 0xe00000, v144
	global_load_dwordx4 v[128:131], v15, s[4:5]
	v_add_u32_e32 v14, 0xe80000, v144
	global_load_dwordx4 v[132:135], v14, s[4:5]
	v_add_u32_e32 v15, 0xf00000, v144
	global_load_dwordx4 v[136:139], v15, s[4:5]
	v_add_u32_e32 v14, 0xf80000, v144
	global_load_dwordx4 v[140:143], v14, s[4:5]
	s_waitcnt vmcnt(16)
	v_readlane_b32 s36, v8, 0
	v_readlane_b32 s37, v8, 1
	v_readlane_b32 s38, v8, 2
	v_readlane_b32 s39, v8, 3
	v_readlane_b32 s40, v8, 4
	v_readlane_b32 s41, v8, 5
	v_readlane_b32 s42, v8, 6
	v_readlane_b32 s43, v8, 7
	v_readlane_b32 s44, v8, 8
	v_readlane_b32 s45, v8, 9
	v_readlane_b32 s52, v8, 10
	v_readlane_b32 s53, v8, 11
	v_readlane_b32 s54, v8, 12
	v_readlane_b32 s55, v8, 13
	v_readlane_b32 s56, v8, 14
	v_readlane_b32 s57, v8, 15
	global_store_dwordx4 v144, v[4:7], s[4:5]
	v_fma_f32 v148, v4, s36, v16
	v_fma_f32 v149, v5, s36, v17
	v_fma_f32 v150, v6, s36, v18
	v_fma_f32 v151, v7, s36, v19
	v_add_u32_e32 v15, 0x80000, v144
	global_store_dwordx4 v15, v[148:151], s[4:5]
	v_fma_f32 v152, v148, s37, v20
	v_fma_f32 v153, v149, s37, v21
	v_fma_f32 v154, v150, s37, v22
	v_fma_f32 v155, v151, s37, v23
	v_add_u32_e32 v14, 0x100000, v144
	global_store_dwordx4 v14, v[152:155], s[4:5]
	v_fma_f32 v156, v152, s38, v24
	v_fma_f32 v157, v153, s38, v25
	v_fma_f32 v158, v154, s38, v26
	v_fma_f32 v159, v155, s38, v27
	v_add_u32_e32 v15, 0x180000, v144
	global_store_dwordx4 v15, v[156:159], s[4:5]
	v_fma_f32 v4, v156, s39, v28
	v_fma_f32 v5, v157, s39, v29
	v_fma_f32 v6, v158, s39, v30
	v_fma_f32 v7, v159, s39, v31
	v_add_u32_e32 v14, 0x200000, v144
	global_store_dwordx4 v14, v[4:7], s[4:5]
	v_fma_f32 v148, v4, s40, v32
	v_fma_f32 v149, v5, s40, v33
	v_fma_f32 v150, v6, s40, v34
	v_fma_f32 v151, v7, s40, v35
	v_add_u32_e32 v15, 0x280000, v144
	global_store_dwordx4 v15, v[148:151], s[4:5]
	v_fma_f32 v152, v148, s41, v36
	v_fma_f32 v153, v149, s41, v37
	v_fma_f32 v154, v150, s41, v38
	v_fma_f32 v155, v151, s41, v39
	v_add_u32_e32 v14, 0x300000, v144
	global_store_dwordx4 v14, v[152:155], s[4:5]
	v_fma_f32 v156, v152, s42, v40
	v_fma_f32 v157, v153, s42, v41
	v_fma_f32 v158, v154, s42, v42
	v_fma_f32 v159, v155, s42, v43
	v_add_u32_e32 v15, 0x380000, v144
	global_store_dwordx4 v15, v[156:159], s[4:5]
	v_fma_f32 v4, v156, s43, v44
	v_fma_f32 v5, v157, s43, v45
	v_fma_f32 v6, v158, s43, v46
	v_fma_f32 v7, v159, s43, v47
	v_add_u32_e32 v14, 0x400000, v144
	global_store_dwordx4 v14, v[4:7], s[4:5]
	v_fma_f32 v148, v4, s44, v48
	v_fma_f32 v149, v5, s44, v49
	v_fma_f32 v150, v6, s44, v50
	v_fma_f32 v151, v7, s44, v51
	v_add_u32_e32 v15, 0x480000, v144
	global_store_dwordx4 v15, v[148:151], s[4:5]
	v_fma_f32 v152, v148, s45, v52
	v_fma_f32 v153, v149, s45, v53
	v_fma_f32 v154, v150, s45, v54
	v_fma_f32 v155, v151, s45, v55
	v_add_u32_e32 v14, 0x500000, v144
	global_store_dwordx4 v14, v[152:155], s[4:5]
	v_fma_f32 v156, v152, s52, v56
	v_fma_f32 v157, v153, s52, v57
	v_fma_f32 v158, v154, s52, v58
	v_fma_f32 v159, v155, s52, v59
	v_add_u32_e32 v15, 0x580000, v144
	global_store_dwordx4 v15, v[156:159], s[4:5]
	v_fma_f32 v4, v156, s53, v60
	v_fma_f32 v5, v157, s53, v61
	v_fma_f32 v6, v158, s53, v62
	v_fma_f32 v7, v159, s53, v63
	v_add_u32_e32 v14, 0x600000, v144
	global_store_dwordx4 v14, v[4:7], s[4:5]
	v_fma_f32 v148, v4, s54, v64
	v_fma_f32 v149, v5, s54, v65
	v_fma_f32 v150, v6, s54, v66
	v_fma_f32 v151, v7, s54, v67
	v_add_u32_e32 v15, 0x680000, v144
	global_store_dwordx4 v15, v[148:151], s[4:5]
	v_fma_f32 v152, v148, s55, v68
	v_fma_f32 v153, v149, s55, v69
	v_fma_f32 v154, v150, s55, v70
	v_fma_f32 v155, v151, s55, v71
	v_add_u32_e32 v14, 0x700000, v144
	global_store_dwordx4 v14, v[152:155], s[4:5]
	v_fma_f32 v156, v152, s56, v72
	v_fma_f32 v157, v153, s56, v73
	v_fma_f32 v158, v154, s56, v74
	v_fma_f32 v159, v155, s56, v75
	v_add_u32_e32 v15, 0x780000, v144
	global_store_dwordx4 v15, v[156:159], s[4:5]
	v_fma_f32 v4, v156, s57, v76
	v_fma_f32 v5, v157, s57, v77
	v_fma_f32 v6, v158, s57, v78
	v_fma_f32 v7, v159, s57, v79
	s_waitcnt vmcnt(32)
; __device__ __forceinline__ void ssd_statepass(const Params& p, int task) {
;     ...
;   for (int c0 = 0; c0 < 128; c0 += 4) {
;     float4 v[4]; float d[4];
; #pragma unroll
;     for (int k = 0; k < 4; k++) { v[k] = *(const float4*)(base + (size_t)(c0 + k) * 131072); d[k] = cd[(c0 + k) * 16]; }
; #pragma unroll
;     for (int k = 0; k < 4; k++) {
;       *(float4*)(base + (size_t)(c0 + k) * 131072) = carry;
;       carry.x = carry.x * d[k] + v[k].x; carry.y = carry.y * d[k] + v[k].y;
;       carry.z = carry.z * d[k] + v[k].z; carry.w = carry.w * d[k] + v[k].w;
;     }
;   }
	v_add_u32_e32 v14, 0x1000000, v144
	global_load_dwordx4 v[16:19], v14, s[4:5]
	v_add_u32_e32 v15, 0x1080000, v144
	global_load_dwordx4 v[20:23], v15, s[4:5]
	v_add_u32_e32 v14, 0x1100000, v144
	global_load_dwordx4 v[24:27], v14, s[4:5]
	v_add_u32_e32 v15, 0x1180000, v144
	global_load_dwordx4 v[28:31], v15, s[4:5]
	v_add_u32_e32 v14, 0x1200000, v144
	global_load_dwordx4 v[32:35], v14, s[4:5]
	v_add_u32_e32 v15, 0x1280000, v144
	global_load_dwordx4 v[36:39], v15, s[4:5]
	v_add_u32_e32 v14, 0x1300000, v144
	global_load_dwordx4 v[40:43], v14, s[4:5]
	v_add_u32_e32 v15, 0x1380000, v144
	global_load_dwordx4 v[44:47], v15, s[4:5]
	v_add_u32_e32 v14, 0x1400000, v144
	global_load_dwordx4 v[48:51], v14, s[4:5]
	v_add_u32_e32 v15, 0x1480000, v144
	global_load_dwordx4 v[52:55], v15, s[4:5]
	v_add_u32_e32 v14, 0x1500000, v144
	global_load_dwordx4 v[56:59], v14, s[4:5]
	v_add_u32_e32 v15, 0x1580000, v144
	global_load_dwordx4 v[60:63], v15, s[4:5]
	v_add_u32_e32 v14, 0x1600000, v144
	global_load_dwordx4 v[64:67], v14, s[4:5]
	v_add_u32_e32 v15, 0x1680000, v144
	global_load_dwordx4 v[68:71], v15, s[4:5]
	v_add_u32_e32 v14, 0x1700000, v144
	global_load_dwordx4 v[72:75], v14, s[4:5]
	v_add_u32_e32 v15, 0x1780000, v144
	global_load_dwordx4 v[76:79], v15, s[4:5]
	s_waitcnt vmcnt(32)
	v_readlane_b32 s36, v8, 16
	v_readlane_b32 s37, v8, 17
	v_readlane_b32 s38, v8, 18
	v_readlane_b32 s39, v8, 19
	v_readlane_b32 s40, v8, 20
	v_readlane_b32 s41, v8, 21
	v_readlane_b32 s42, v8, 22
	v_readlane_b32 s43, v8, 23
	v_readlane_b32 s44, v8, 24
	v_readlane_b32 s45, v8, 25
	v_readlane_b32 s52, v8, 26
	v_readlane_b32 s53, v8, 27
	v_readlane_b32 s54, v8, 28
	v_readlane_b32 s55, v8, 29
	v_readlane_b32 s56, v8, 30
	v_readlane_b32 s57, v8, 31
	v_add_u32_e32 v14, 0x800000, v144
	global_store_dwordx4 v14, v[4:7], s[4:5]
	v_fma_f32 v148, v4, s36, v80
	v_fma_f32 v149, v5, s36, v81
	v_fma_f32 v150, v6, s36, v82
	v_fma_f32 v151, v7, s36, v83
	v_add_u32_e32 v15, 0x880000, v144
	global_store_dwordx4 v15, v[148:151], s[4:5]
	v_fma_f32 v152, v148, s37, v84
	v_fma_f32 v153, v149, s37, v85
	v_fma_f32 v154, v150, s37, v86
	v_fma_f32 v155, v151, s37, v87
	v_add_u32_e32 v14, 0x900000, v144
	global_store_dwordx4 v14, v[152:155], s[4:5]
	v_fma_f32 v156, v152, s38, v88
	v_fma_f32 v157, v153, s38, v89
	v_fma_f32 v158, v154, s38, v90
	v_fma_f32 v159, v155, s38, v91
	v_add_u32_e32 v15, 0x980000, v144
	global_store_dwordx4 v15, v[156:159], s[4:5]
	v_fma_f32 v4, v156, s39, v92
	v_fma_f32 v5, v157, s39, v93
	v_fma_f32 v6, v158, s39, v94
	v_fma_f32 v7, v159, s39, v95
	v_add_u32_e32 v14, 0xa00000, v144
	global_store_dwordx4 v14, v[4:7], s[4:5]
	v_fma_f32 v148, v4, s40, v96
	v_fma_f32 v149, v5, s40, v97
	v_fma_f32 v150, v6, s40, v98
	v_fma_f32 v151, v7, s40, v99
	v_add_u32_e32 v15, 0xa80000, v144
	global_store_dwordx4 v15, v[148:151], s[4:5]
	v_fma_f32 v152, v148, s41, v100
	v_fma_f32 v153, v149, s41, v101
	v_fma_f32 v154, v150, s41, v102
	v_fma_f32 v155, v151, s41, v103
	v_add_u32_e32 v14, 0xb00000, v144
	global_store_dwordx4 v14, v[152:155], s[4:5]
	v_fma_f32 v156, v152, s42, v104
	v_fma_f32 v157, v153, s42, v105
	v_fma_f32 v158, v154, s42, v106
	v_fma_f32 v159, v155, s42, v107
	v_add_u32_e32 v15, 0xb80000, v144
	global_store_dwordx4 v15, v[156:159], s[4:5]
	v_fma_f32 v4, v156, s43, v108
	v_fma_f32 v5, v157, s43, v109
	v_fma_f32 v6, v158, s43, v110
	v_fma_f32 v7, v159, s43, v111
	v_add_u32_e32 v14, 0xc00000, v144
	global_store_dwordx4 v14, v[4:7], s[4:5]
	v_fma_f32 v148, v4, s44, v112
	v_fma_f32 v149, v5, s44, v113
	v_fma_f32 v150, v6, s44, v114
	v_fma_f32 v151, v7, s44, v115
	v_add_u32_e32 v15, 0xc80000, v144
	global_store_dwordx4 v15, v[148:151], s[4:5]
	v_fma_f32 v152, v148, s45, v116
	v_fma_f32 v153, v149, s45, v117
	v_fma_f32 v154, v150, s45, v118
	v_fma_f32 v155, v151, s45, v119
	v_add_u32_e32 v14, 0xd00000, v144
	global_store_dwordx4 v14, v[152:155], s[4:5]
	v_fma_f32 v156, v152, s52, v120
	v_fma_f32 v157, v153, s52, v121
	v_fma_f32 v158, v154, s52, v122
	v_fma_f32 v159, v155, s52, v123
	v_add_u32_e32 v15, 0xd80000, v144
	global_store_dwordx4 v15, v[156:159], s[4:5]
	v_fma_f32 v4, v156, s53, v124
	v_fma_f32 v5, v157, s53, v125
	v_fma_f32 v6, v158, s53, v126
	v_fma_f32 v7, v159, s53, v127
	v_add_u32_e32 v14, 0xe00000, v144
	global_store_dwordx4 v14, v[4:7], s[4:5]
	v_fma_f32 v148, v4, s54, v128
	v_fma_f32 v149, v5, s54, v129
	v_fma_f32 v150, v6, s54, v130
	v_fma_f32 v151, v7, s54, v131
	v_add_u32_e32 v15, 0xe80000, v144
	global_store_dwordx4 v15, v[148:151], s[4:5]
	v_fma_f32 v152, v148, s55, v132
	v_fma_f32 v153, v149, s55, v133
	v_fma_f32 v154, v150, s55, v134
	v_fma_f32 v155, v151, s55, v135
	v_add_u32_e32 v14, 0xf00000, v144
	global_store_dwordx4 v14, v[152:155], s[4:5]
	v_fma_f32 v156, v152, s56, v136
	v_fma_f32 v157, v153, s56, v137
	v_fma_f32 v158, v154, s56, v138
	v_fma_f32 v159, v155, s56, v139
	v_add_u32_e32 v15, 0xf80000, v144
	global_store_dwordx4 v15, v[156:159], s[4:5]
	v_fma_f32 v4, v156, s57, v140
	v_fma_f32 v5, v157, s57, v141
	v_fma_f32 v6, v158, s57, v142
	v_fma_f32 v7, v159, s57, v143
	s_waitcnt vmcnt(32)
; __device__ __forceinline__ void ssd_statepass(const Params& p, int task) {
;     ...
;   for (int c0 = 0; c0 < 128; c0 += 4) {
;     float4 v[4]; float d[4];
; #pragma unroll
;     for (int k = 0; k < 4; k++) { v[k] = *(const float4*)(base + (size_t)(c0 + k) * 131072); d[k] = cd[(c0 + k) * 16]; }
; #pragma unroll
;     for (int k = 0; k < 4; k++) {
;       *(float4*)(base + (size_t)(c0 + k) * 131072) = carry;
;       carry.x = carry.x * d[k] + v[k].x; carry.y = carry.y * d[k] + v[k].y;
;       carry.z = carry.z * d[k] + v[k].z; carry.w = carry.w * d[k] + v[k].w;
;     }
;   }
	v_add_u32_e32 v14, 0x1800000, v144
	global_load_dwordx4 v[80:83], v14, s[4:5]
	v_add_u32_e32 v15, 0x1880000, v144
	global_load_dwordx4 v[84:87], v15, s[4:5]
	v_add_u32_e32 v14, 0x1900000, v144
	global_load_dwordx4 v[88:91], v14, s[4:5]
	v_add_u32_e32 v15, 0x1980000, v144
	global_load_dwordx4 v[92:95], v15, s[4:5]
	v_add_u32_e32 v14, 0x1a00000, v144
	global_load_dwordx4 v[96:99], v14, s[4:5]
	v_add_u32_e32 v15, 0x1a80000, v144
	global_load_dwordx4 v[100:103], v15, s[4:5]
	v_add_u32_e32 v14, 0x1b00000, v144
	global_load_dwordx4 v[104:107], v14, s[4:5]
	v_add_u32_e32 v15, 0x1b80000, v144
	global_load_dwordx4 v[108:111], v15, s[4:5]
	v_add_u32_e32 v14, 0x1c00000, v144
	global_load_dwordx4 v[112:115], v14, s[4:5]
	v_add_u32_e32 v15, 0x1c80000, v144
	global_load_dwordx4 v[116:119], v15, s[4:5]
	v_add_u32_e32 v14, 0x1d00000, v144
	global_load_dwordx4 v[120:123], v14, s[4:5]
	v_add_u32_e32 v15, 0x1d80000, v144
	global_load_dwordx4 v[124:127], v15, s[4:5]
	v_add_u32_e32 v14, 0x1e00000, v144
	global_load_dwordx4 v[128:131], v14, s[4:5]
	v_add_u32_e32 v15, 0x1e80000, v144
	global_load_dwordx4 v[132:135], v15, s[4:5]
	v_add_u32_e32 v14, 0x1f00000, v144
	global_load_dwordx4 v[136:139], v14, s[4:5]
	v_add_u32_e32 v15, 0x1f80000, v144
	global_load_dwordx4 v[140:143], v15, s[4:5]
	s_waitcnt vmcnt(32)
	v_readlane_b32 s36, v8, 32
	v_readlane_b32 s37, v8, 33
	v_readlane_b32 s38, v8, 34
	v_readlane_b32 s39, v8, 35
	v_readlane_b32 s40, v8, 36
	v_readlane_b32 s41, v8, 37
	v_readlane_b32 s42, v8, 38
	v_readlane_b32 s43, v8, 39
	v_readlane_b32 s44, v8, 40
	v_readlane_b32 s45, v8, 41
	v_readlane_b32 s52, v8, 42
	v_readlane_b32 s53, v8, 43
	v_readlane_b32 s54, v8, 44
	v_readlane_b32 s55, v8, 45
	v_readlane_b32 s56, v8, 46
	v_readlane_b32 s57, v8, 47
	v_add_u32_e32 v14, 0x1000000, v144
	global_store_dwordx4 v14, v[4:7], s[4:5]
	v_fma_f32 v148, v4, s36, v16
	v_fma_f32 v149, v5, s36, v17
	v_fma_f32 v150, v6, s36, v18
	v_fma_f32 v151, v7, s36, v19
	v_add_u32_e32 v15, 0x1080000, v144
	global_store_dwordx4 v15, v[148:151], s[4:5]
	v_fma_f32 v152, v148, s37, v20
	v_fma_f32 v153, v149, s37, v21
	v_fma_f32 v154, v150, s37, v22
	v_fma_f32 v155, v151, s37, v23
	v_add_u32_e32 v14, 0x1100000, v144
	global_store_dwordx4 v14, v[152:155], s[4:5]
	v_fma_f32 v156, v152, s38, v24
	v_fma_f32 v157, v153, s38, v25
	v_fma_f32 v158, v154, s38, v26
	v_fma_f32 v159, v155, s38, v27
	v_add_u32_e32 v15, 0x1180000, v144
	global_store_dwordx4 v15, v[156:159], s[4:5]
	v_fma_f32 v4, v156, s39, v28
	v_fma_f32 v5, v157, s39, v29
	v_fma_f32 v6, v158, s39, v30
	v_fma_f32 v7, v159, s39, v31
	v_add_u32_e32 v14, 0x1200000, v144
	global_store_dwordx4 v14, v[4:7], s[4:5]
	v_fma_f32 v148, v4, s40, v32
	v_fma_f32 v149, v5, s40, v33
	v_fma_f32 v150, v6, s40, v34
	v_fma_f32 v151, v7, s40, v35
	v_add_u32_e32 v15, 0x1280000, v144
	global_store_dwordx4 v15, v[148:151], s[4:5]
	v_fma_f32 v152, v148, s41, v36
	v_fma_f32 v153, v149, s41, v37
	v_fma_f32 v154, v150, s41, v38
	v_fma_f32 v155, v151, s41, v39
	v_add_u32_e32 v14, 0x1300000, v144
	global_store_dwordx4 v14, v[152:155], s[4:5]
	v_fma_f32 v156, v152, s42, v40
	v_fma_f32 v157, v153, s42, v41
	v_fma_f32 v158, v154, s42, v42
	v_fma_f32 v159, v155, s42, v43
	v_add_u32_e32 v15, 0x1380000, v144
	global_store_dwordx4 v15, v[156:159], s[4:5]
	v_fma_f32 v4, v156, s43, v44
	v_fma_f32 v5, v157, s43, v45
	v_fma_f32 v6, v158, s43, v46
	v_fma_f32 v7, v159, s43, v47
	v_add_u32_e32 v14, 0x1400000, v144
	global_store_dwordx4 v14, v[4:7], s[4:5]
	v_fma_f32 v148, v4, s44, v48
	v_fma_f32 v149, v5, s44, v49
	v_fma_f32 v150, v6, s44, v50
	v_fma_f32 v151, v7, s44, v51
	v_add_u32_e32 v15, 0x1480000, v144
	global_store_dwordx4 v15, v[148:151], s[4:5]
	v_fma_f32 v152, v148, s45, v52
	v_fma_f32 v153, v149, s45, v53
	v_fma_f32 v154, v150, s45, v54
	v_fma_f32 v155, v151, s45, v55
	v_add_u32_e32 v14, 0x1500000, v144
	global_store_dwordx4 v14, v[152:155], s[4:5]
	v_fma_f32 v156, v152, s52, v56
	v_fma_f32 v157, v153, s52, v57
	v_fma_f32 v158, v154, s52, v58
	v_fma_f32 v159, v155, s52, v59
	v_add_u32_e32 v15, 0x1580000, v144
	global_store_dwordx4 v15, v[156:159], s[4:5]
	v_fma_f32 v4, v156, s53, v60
	v_fma_f32 v5, v157, s53, v61
	v_fma_f32 v6, v158, s53, v62
	v_fma_f32 v7, v159, s53, v63
	v_add_u32_e32 v14, 0x1600000, v144
	global_store_dwordx4 v14, v[4:7], s[4:5]
	v_fma_f32 v148, v4, s54, v64
	v_fma_f32 v149, v5, s54, v65
	v_fma_f32 v150, v6, s54, v66
	v_fma_f32 v151, v7, s54, v67
	v_add_u32_e32 v15, 0x1680000, v144
	global_store_dwordx4 v15, v[148:151], s[4:5]
	v_fma_f32 v152, v148, s55, v68
	v_fma_f32 v153, v149, s55, v69
	v_fma_f32 v154, v150, s55, v70
	v_fma_f32 v155, v151, s55, v71
	v_add_u32_e32 v14, 0x1700000, v144
	global_store_dwordx4 v14, v[152:155], s[4:5]
	v_fma_f32 v156, v152, s56, v72
	v_fma_f32 v157, v153, s56, v73
	v_fma_f32 v158, v154, s56, v74
	v_fma_f32 v159, v155, s56, v75
	v_add_u32_e32 v15, 0x1780000, v144
	global_store_dwordx4 v15, v[156:159], s[4:5]
	v_fma_f32 v4, v156, s57, v76
	v_fma_f32 v5, v157, s57, v77
	v_fma_f32 v6, v158, s57, v78
	v_fma_f32 v7, v159, s57, v79
	s_waitcnt vmcnt(32)
; __device__ __forceinline__ void ssd_statepass(const Params& p, int task) {
;     ...
;   for (int c0 = 0; c0 < 128; c0 += 4) {
;     float4 v[4]; float d[4];
; #pragma unroll
;     for (int k = 0; k < 4; k++) { v[k] = *(const float4*)(base + (size_t)(c0 + k) * 131072); d[k] = cd[(c0 + k) * 16]; }
; #pragma unroll
;     for (int k = 0; k < 4; k++) {
;       *(float4*)(base + (size_t)(c0 + k) * 131072) = carry;
;       carry.x = carry.x * d[k] + v[k].x; carry.y = carry.y * d[k] + v[k].y;
;       carry.z = carry.z * d[k] + v[k].z; carry.w = carry.w * d[k] + v[k].w;
;     }
;   }
	v_add_u32_e32 v14, 0x2000000, v144
	global_load_dwordx4 v[16:19], v14, s[4:5]
	v_add_u32_e32 v15, 0x2080000, v144
	global_load_dwordx4 v[20:23], v15, s[4:5]
	v_add_u32_e32 v14, 0x2100000, v144
	global_load_dwordx4 v[24:27], v14, s[4:5]
	v_add_u32_e32 v15, 0x2180000, v144
	global_load_dwordx4 v[28:31], v15, s[4:5]
	v_add_u32_e32 v14, 0x2200000, v144
	global_load_dwordx4 v[32:35], v14, s[4:5]
	v_add_u32_e32 v15, 0x2280000, v144
	global_load_dwordx4 v[36:39], v15, s[4:5]
	v_add_u32_e32 v14, 0x2300000, v144
	global_load_dwordx4 v[40:43], v14, s[4:5]
	v_add_u32_e32 v15, 0x2380000, v144
	global_load_dwordx4 v[44:47], v15, s[4:5]
	v_add_u32_e32 v14, 0x2400000, v144
	global_load_dwordx4 v[48:51], v14, s[4:5]
	v_add_u32_e32 v15, 0x2480000, v144
	global_load_dwordx4 v[52:55], v15, s[4:5]
	v_add_u32_e32 v14, 0x2500000, v144
	global_load_dwordx4 v[56:59], v14, s[4:5]
	v_add_u32_e32 v15, 0x2580000, v144
	global_load_dwordx4 v[60:63], v15, s[4:5]
	v_add_u32_e32 v14, 0x2600000, v144
	global_load_dwordx4 v[64:67], v14, s[4:5]
	v_add_u32_e32 v15, 0x2680000, v144
	global_load_dwordx4 v[68:71], v15, s[4:5]
	v_add_u32_e32 v14, 0x2700000, v144
	global_load_dwordx4 v[72:75], v14, s[4:5]
	v_add_u32_e32 v15, 0x2780000, v144
	global_load_dwordx4 v[76:79], v15, s[4:5]
	s_waitcnt vmcnt(32)
	v_readlane_b32 s36, v8, 48
	v_readlane_b32 s37, v8, 49
	v_readlane_b32 s38, v8, 50
	v_readlane_b32 s39, v8, 51
	v_readlane_b32 s40, v8, 52
	v_readlane_b32 s41, v8, 53
	v_readlane_b32 s42, v8, 54
	v_readlane_b32 s43, v8, 55
	v_readlane_b32 s44, v8, 56
	v_readlane_b32 s45, v8, 57
	v_readlane_b32 s52, v8, 58
	v_readlane_b32 s53, v8, 59
	v_readlane_b32 s54, v8, 60
	v_readlane_b32 s55, v8, 61
	v_readlane_b32 s56, v8, 62
	v_readlane_b32 s57, v8, 63
	v_add_u32_e32 v14, 0x1800000, v144
	global_store_dwordx4 v14, v[4:7], s[4:5]
	v_fma_f32 v148, v4, s36, v80
	v_fma_f32 v149, v5, s36, v81
	v_fma_f32 v150, v6, s36, v82
	v_fma_f32 v151, v7, s36, v83
	v_add_u32_e32 v15, 0x1880000, v144
	global_store_dwordx4 v15, v[148:151], s[4:5]
	v_fma_f32 v152, v148, s37, v84
	v_fma_f32 v153, v149, s37, v85
	v_fma_f32 v154, v150, s37, v86
	v_fma_f32 v155, v151, s37, v87
	v_add_u32_e32 v14, 0x1900000, v144
	global_store_dwordx4 v14, v[152:155], s[4:5]
	v_fma_f32 v156, v152, s38, v88
	v_fma_f32 v157, v153, s38, v89
	v_fma_f32 v158, v154, s38, v90
	v_fma_f32 v159, v155, s38, v91
	v_add_u32_e32 v15, 0x1980000, v144
	global_store_dwordx4 v15, v[156:159], s[4:5]
	v_fma_f32 v4, v156, s39, v92
	v_fma_f32 v5, v157, s39, v93
	v_fma_f32 v6, v158, s39, v94
	v_fma_f32 v7, v159, s39, v95
	v_add_u32_e32 v14, 0x1a00000, v144
	global_store_dwordx4 v14, v[4:7], s[4:5]
	v_fma_f32 v148, v4, s40, v96
	v_fma_f32 v149, v5, s40, v97
	v_fma_f32 v150, v6, s40, v98
	v_fma_f32 v151, v7, s40, v99
	v_add_u32_e32 v15, 0x1a80000, v144
	global_store_dwordx4 v15, v[148:151], s[4:5]
	v_fma_f32 v152, v148, s41, v100
	v_fma_f32 v153, v149, s41, v101
	v_fma_f32 v154, v150, s41, v102
	v_fma_f32 v155, v151, s41, v103
	v_add_u32_e32 v14, 0x1b00000, v144
	global_store_dwordx4 v14, v[152:155], s[4:5]
	v_fma_f32 v156, v152, s42, v104
	v_fma_f32 v157, v153, s42, v105
	v_fma_f32 v158, v154, s42, v106
	v_fma_f32 v159, v155, s42, v107
	v_add_u32_e32 v15, 0x1b80000, v144
	global_store_dwordx4 v15, v[156:159], s[4:5]
	v_fma_f32 v4, v156, s43, v108
	v_fma_f32 v5, v157, s43, v109
	v_fma_f32 v6, v158, s43, v110
	v_fma_f32 v7, v159, s43, v111
	v_add_u32_e32 v14, 0x1c00000, v144
	global_store_dwordx4 v14, v[4:7], s[4:5]
	v_fma_f32 v148, v4, s44, v112
	v_fma_f32 v149, v5, s44, v113
	v_fma_f32 v150, v6, s44, v114
	v_fma_f32 v151, v7, s44, v115
	v_add_u32_e32 v15, 0x1c80000, v144
	global_store_dwordx4 v15, v[148:151], s[4:5]
	v_fma_f32 v152, v148, s45, v116
	v_fma_f32 v153, v149, s45, v117
	v_fma_f32 v154, v150, s45, v118
	v_fma_f32 v155, v151, s45, v119
	v_add_u32_e32 v14, 0x1d00000, v144
	global_store_dwordx4 v14, v[152:155], s[4:5]
	v_fma_f32 v156, v152, s52, v120
	v_fma_f32 v157, v153, s52, v121
	v_fma_f32 v158, v154, s52, v122
	v_fma_f32 v159, v155, s52, v123
	v_add_u32_e32 v15, 0x1d80000, v144
	global_store_dwordx4 v15, v[156:159], s[4:5]
	v_fma_f32 v4, v156, s53, v124
	v_fma_f32 v5, v157, s53, v125
	v_fma_f32 v6, v158, s53, v126
	v_fma_f32 v7, v159, s53, v127
	v_add_u32_e32 v14, 0x1e00000, v144
	global_store_dwordx4 v14, v[4:7], s[4:5]
	v_fma_f32 v148, v4, s54, v128
	v_fma_f32 v149, v5, s54, v129
	v_fma_f32 v150, v6, s54, v130
	v_fma_f32 v151, v7, s54, v131
	v_add_u32_e32 v15, 0x1e80000, v144
	global_store_dwordx4 v15, v[148:151], s[4:5]
	v_fma_f32 v152, v148, s55, v132
	v_fma_f32 v153, v149, s55, v133
	v_fma_f32 v154, v150, s55, v134
	v_fma_f32 v155, v151, s55, v135
	v_add_u32_e32 v14, 0x1f00000, v144
	global_store_dwordx4 v14, v[152:155], s[4:5]
	v_fma_f32 v156, v152, s56, v136
	v_fma_f32 v157, v153, s56, v137
	v_fma_f32 v158, v154, s56, v138
	v_fma_f32 v159, v155, s56, v139
	v_add_u32_e32 v15, 0x1f80000, v144
	global_store_dwordx4 v15, v[156:159], s[4:5]
	v_fma_f32 v4, v156, s57, v140
	v_fma_f32 v5, v157, s57, v141
	v_fma_f32 v6, v158, s57, v142
	v_fma_f32 v7, v159, s57, v143
	s_waitcnt vmcnt(32)
; __device__ __forceinline__ void ssd_statepass(const Params& p, int task) {
;     ...
;   for (int c0 = 0; c0 < 128; c0 += 4) {
;     float4 v[4]; float d[4];
; #pragma unroll
;     for (int k = 0; k < 4; k++) { v[k] = *(const float4*)(base + (size_t)(c0 + k) * 131072); d[k] = cd[(c0 + k) * 16]; }
; #pragma unroll
;     for (int k = 0; k < 4; k++) {
;       *(float4*)(base + (size_t)(c0 + k) * 131072) = carry;
;       carry.x = carry.x * d[k] + v[k].x; carry.y = carry.y * d[k] + v[k].y;
;       carry.z = carry.z * d[k] + v[k].z; carry.w = carry.w * d[k] + v[k].w;
;     }
;   }
	v_add_u32_e32 v14, 0x2800000, v144
	global_load_dwordx4 v[80:83], v14, s[4:5]
	v_add_u32_e32 v15, 0x2880000, v144
	global_load_dwordx4 v[84:87], v15, s[4:5]
	v_add_u32_e32 v14, 0x2900000, v144
	global_load_dwordx4 v[88:91], v14, s[4:5]
	v_add_u32_e32 v15, 0x2980000, v144
	global_load_dwordx4 v[92:95], v15, s[4:5]
	v_add_u32_e32 v14, 0x2a00000, v144
	global_load_dwordx4 v[96:99], v14, s[4:5]
	v_add_u32_e32 v15, 0x2a80000, v144
	global_load_dwordx4 v[100:103], v15, s[4:5]
	v_add_u32_e32 v14, 0x2b00000, v144
	global_load_dwordx4 v[104:107], v14, s[4:5]
	v_add_u32_e32 v15, 0x2b80000, v144
	global_load_dwordx4 v[108:111], v15, s[4:5]
	v_add_u32_e32 v14, 0x2c00000, v144
	global_load_dwordx4 v[112:115], v14, s[4:5]
	v_add_u32_e32 v15, 0x2c80000, v144
	global_load_dwordx4 v[116:119], v15, s[4:5]
	v_add_u32_e32 v14, 0x2d00000, v144
	global_load_dwordx4 v[120:123], v14, s[4:5]
	v_add_u32_e32 v15, 0x2d80000, v144
	global_load_dwordx4 v[124:127], v15, s[4:5]
	v_add_u32_e32 v14, 0x2e00000, v144
	global_load_dwordx4 v[128:131], v14, s[4:5]
	v_add_u32_e32 v15, 0x2e80000, v144
	global_load_dwordx4 v[132:135], v15, s[4:5]
	v_add_u32_e32 v14, 0x2f00000, v144
	global_load_dwordx4 v[136:139], v14, s[4:5]
	v_add_u32_e32 v15, 0x2f80000, v144
	global_load_dwordx4 v[140:143], v15, s[4:5]
	s_waitcnt vmcnt(32)
	v_readlane_b32 s36, v9, 0
	v_readlane_b32 s37, v9, 1
	v_readlane_b32 s38, v9, 2
	v_readlane_b32 s39, v9, 3
	v_readlane_b32 s40, v9, 4
	v_readlane_b32 s41, v9, 5
	v_readlane_b32 s42, v9, 6
	v_readlane_b32 s43, v9, 7
	v_readlane_b32 s44, v9, 8
	v_readlane_b32 s45, v9, 9
	v_readlane_b32 s52, v9, 10
	v_readlane_b32 s53, v9, 11
	v_readlane_b32 s54, v9, 12
	v_readlane_b32 s55, v9, 13
	v_readlane_b32 s56, v9, 14
	v_readlane_b32 s57, v9, 15
	v_add_u32_e32 v14, 0x2000000, v144
	global_store_dwordx4 v14, v[4:7], s[4:5]
	v_fma_f32 v148, v4, s36, v16
	v_fma_f32 v149, v5, s36, v17
	v_fma_f32 v150, v6, s36, v18
	v_fma_f32 v151, v7, s36, v19
	v_add_u32_e32 v15, 0x2080000, v144
	global_store_dwordx4 v15, v[148:151], s[4:5]
	v_fma_f32 v152, v148, s37, v20
	v_fma_f32 v153, v149, s37, v21
	v_fma_f32 v154, v150, s37, v22
	v_fma_f32 v155, v151, s37, v23
	v_add_u32_e32 v14, 0x2100000, v144
	global_store_dwordx4 v14, v[152:155], s[4:5]
	v_fma_f32 v156, v152, s38, v24
	v_fma_f32 v157, v153, s38, v25
	v_fma_f32 v158, v154, s38, v26
	v_fma_f32 v159, v155, s38, v27
	v_add_u32_e32 v15, 0x2180000, v144
	global_store_dwordx4 v15, v[156:159], s[4:5]
	v_fma_f32 v4, v156, s39, v28
	v_fma_f32 v5, v157, s39, v29
	v_fma_f32 v6, v158, s39, v30
	v_fma_f32 v7, v159, s39, v31
	v_add_u32_e32 v14, 0x2200000, v144
	global_store_dwordx4 v14, v[4:7], s[4:5]
	v_fma_f32 v148, v4, s40, v32
	v_fma_f32 v149, v5, s40, v33
	v_fma_f32 v150, v6, s40, v34
	v_fma_f32 v151, v7, s40, v35
	v_add_u32_e32 v15, 0x2280000, v144
	global_store_dwordx4 v15, v[148:151], s[4:5]
	v_fma_f32 v152, v148, s41, v36
	v_fma_f32 v153, v149, s41, v37
	v_fma_f32 v154, v150, s41, v38
	v_fma_f32 v155, v151, s41, v39
	v_add_u32_e32 v14, 0x2300000, v144
	global_store_dwordx4 v14, v[152:155], s[4:5]
	v_fma_f32 v156, v152, s42, v40
	v_fma_f32 v157, v153, s42, v41
	v_fma_f32 v158, v154, s42, v42
	v_fma_f32 v159, v155, s42, v43
	v_add_u32_e32 v15, 0x2380000, v144
	global_store_dwordx4 v15, v[156:159], s[4:5]
	v_fma_f32 v4, v156, s43, v44
	v_fma_f32 v5, v157, s43, v45
	v_fma_f32 v6, v158, s43, v46
	v_fma_f32 v7, v159, s43, v47
	v_add_u32_e32 v14, 0x2400000, v144
	global_store_dwordx4 v14, v[4:7], s[4:5]
	v_fma_f32 v148, v4, s44, v48
	v_fma_f32 v149, v5, s44, v49
	v_fma_f32 v150, v6, s44, v50
	v_fma_f32 v151, v7, s44, v51
	v_add_u32_e32 v15, 0x2480000, v144
	global_store_dwordx4 v15, v[148:151], s[4:5]
	v_fma_f32 v152, v148, s45, v52
	v_fma_f32 v153, v149, s45, v53
	v_fma_f32 v154, v150, s45, v54
	v_fma_f32 v155, v151, s45, v55
	v_add_u32_e32 v14, 0x2500000, v144
	global_store_dwordx4 v14, v[152:155], s[4:5]
	v_fma_f32 v156, v152, s52, v56
	v_fma_f32 v157, v153, s52, v57
	v_fma_f32 v158, v154, s52, v58
	v_fma_f32 v159, v155, s52, v59
	v_add_u32_e32 v15, 0x2580000, v144
	global_store_dwordx4 v15, v[156:159], s[4:5]
	v_fma_f32 v4, v156, s53, v60
	v_fma_f32 v5, v157, s53, v61
	v_fma_f32 v6, v158, s53, v62
	v_fma_f32 v7, v159, s53, v63
	v_add_u32_e32 v14, 0x2600000, v144
	global_store_dwordx4 v14, v[4:7], s[4:5]
	v_fma_f32 v148, v4, s54, v64
	v_fma_f32 v149, v5, s54, v65
	v_fma_f32 v150, v6, s54, v66
	v_fma_f32 v151, v7, s54, v67
	v_add_u32_e32 v15, 0x2680000, v144
	global_store_dwordx4 v15, v[148:151], s[4:5]
	v_fma_f32 v152, v148, s55, v68
	v_fma_f32 v153, v149, s55, v69
	v_fma_f32 v154, v150, s55, v70
	v_fma_f32 v155, v151, s55, v71
	v_add_u32_e32 v14, 0x2700000, v144
	global_store_dwordx4 v14, v[152:155], s[4:5]
	v_fma_f32 v156, v152, s56, v72
	v_fma_f32 v157, v153, s56, v73
	v_fma_f32 v158, v154, s56, v74
	v_fma_f32 v159, v155, s56, v75
	v_add_u32_e32 v15, 0x2780000, v144
	global_store_dwordx4 v15, v[156:159], s[4:5]
	v_fma_f32 v4, v156, s57, v76
	v_fma_f32 v5, v157, s57, v77
	v_fma_f32 v6, v158, s57, v78
	v_fma_f32 v7, v159, s57, v79
	s_waitcnt vmcnt(32)
; __device__ __forceinline__ void ssd_statepass(const Params& p, int task) {
;     ...
;   for (int c0 = 0; c0 < 128; c0 += 4) {
;     float4 v[4]; float d[4];
; #pragma unroll
;     for (int k = 0; k < 4; k++) { v[k] = *(const float4*)(base + (size_t)(c0 + k) * 131072); d[k] = cd[(c0 + k) * 16]; }
; #pragma unroll
;     for (int k = 0; k < 4; k++) {
;       *(float4*)(base + (size_t)(c0 + k) * 131072) = carry;
;       carry.x = carry.x * d[k] + v[k].x; carry.y = carry.y * d[k] + v[k].y;
;       carry.z = carry.z * d[k] + v[k].z; carry.w = carry.w * d[k] + v[k].w;
;     }
;   }
	v_add_u32_e32 v14, 0x3000000, v144
	global_load_dwordx4 v[16:19], v14, s[4:5]
	v_add_u32_e32 v15, 0x3080000, v144
	global_load_dwordx4 v[20:23], v15, s[4:5]
	v_add_u32_e32 v14, 0x3100000, v144
	global_load_dwordx4 v[24:27], v14, s[4:5]
	v_add_u32_e32 v15, 0x3180000, v144
	global_load_dwordx4 v[28:31], v15, s[4:5]
	v_add_u32_e32 v14, 0x3200000, v144
	global_load_dwordx4 v[32:35], v14, s[4:5]
	v_add_u32_e32 v15, 0x3280000, v144
	global_load_dwordx4 v[36:39], v15, s[4:5]
	v_add_u32_e32 v14, 0x3300000, v144
	global_load_dwordx4 v[40:43], v14, s[4:5]
	v_add_u32_e32 v15, 0x3380000, v144
	global_load_dwordx4 v[44:47], v15, s[4:5]
	v_add_u32_e32 v14, 0x3400000, v144
	global_load_dwordx4 v[48:51], v14, s[4:5]
	v_add_u32_e32 v15, 0x3480000, v144
	global_load_dwordx4 v[52:55], v15, s[4:5]
	v_add_u32_e32 v14, 0x3500000, v144
	global_load_dwordx4 v[56:59], v14, s[4:5]
	v_add_u32_e32 v15, 0x3580000, v144
	global_load_dwordx4 v[60:63], v15, s[4:5]
	v_add_u32_e32 v14, 0x3600000, v144
	global_load_dwordx4 v[64:67], v14, s[4:5]
	v_add_u32_e32 v15, 0x3680000, v144
	global_load_dwordx4 v[68:71], v15, s[4:5]
	v_add_u32_e32 v14, 0x3700000, v144
	global_load_dwordx4 v[72:75], v14, s[4:5]
	v_add_u32_e32 v15, 0x3780000, v144
	global_load_dwordx4 v[76:79], v15, s[4:5]
	s_waitcnt vmcnt(32)
	v_readlane_b32 s36, v9, 16
	v_readlane_b32 s37, v9, 17
	v_readlane_b32 s38, v9, 18
	v_readlane_b32 s39, v9, 19
	v_readlane_b32 s40, v9, 20
	v_readlane_b32 s41, v9, 21
	v_readlane_b32 s42, v9, 22
	v_readlane_b32 s43, v9, 23
	v_readlane_b32 s44, v9, 24
	v_readlane_b32 s45, v9, 25
	v_readlane_b32 s52, v9, 26
	v_readlane_b32 s53, v9, 27
	v_readlane_b32 s54, v9, 28
	v_readlane_b32 s55, v9, 29
	v_readlane_b32 s56, v9, 30
	v_readlane_b32 s57, v9, 31
	v_add_u32_e32 v14, 0x2800000, v144
	global_store_dwordx4 v14, v[4:7], s[4:5]
	v_fma_f32 v148, v4, s36, v80
	v_fma_f32 v149, v5, s36, v81
	v_fma_f32 v150, v6, s36, v82
	v_fma_f32 v151, v7, s36, v83
	v_add_u32_e32 v15, 0x2880000, v144
	global_store_dwordx4 v15, v[148:151], s[4:5]
	v_fma_f32 v152, v148, s37, v84
	v_fma_f32 v153, v149, s37, v85
	v_fma_f32 v154, v150, s37, v86
	v_fma_f32 v155, v151, s37, v87
	v_add_u32_e32 v14, 0x2900000, v144
	global_store_dwordx4 v14, v[152:155], s[4:5]
	v_fma_f32 v156, v152, s38, v88
	v_fma_f32 v157, v153, s38, v89
	v_fma_f32 v158, v154, s38, v90
	v_fma_f32 v159, v155, s38, v91
	v_add_u32_e32 v15, 0x2980000, v144
	global_store_dwordx4 v15, v[156:159], s[4:5]
	v_fma_f32 v4, v156, s39, v92
	v_fma_f32 v5, v157, s39, v93
	v_fma_f32 v6, v158, s39, v94
	v_fma_f32 v7, v159, s39, v95
	v_add_u32_e32 v14, 0x2a00000, v144
	global_store_dwordx4 v14, v[4:7], s[4:5]
	v_fma_f32 v148, v4, s40, v96
	v_fma_f32 v149, v5, s40, v97
	v_fma_f32 v150, v6, s40, v98
	v_fma_f32 v151, v7, s40, v99
	v_add_u32_e32 v15, 0x2a80000, v144
	global_store_dwordx4 v15, v[148:151], s[4:5]
	v_fma_f32 v152, v148, s41, v100
	v_fma_f32 v153, v149, s41, v101
	v_fma_f32 v154, v150, s41, v102
	v_fma_f32 v155, v151, s41, v103
	v_add_u32_e32 v14, 0x2b00000, v144
	global_store_dwordx4 v14, v[152:155], s[4:5]
	v_fma_f32 v156, v152, s42, v104
	v_fma_f32 v157, v153, s42, v105
	v_fma_f32 v158, v154, s42, v106
	v_fma_f32 v159, v155, s42, v107
	v_add_u32_e32 v15, 0x2b80000, v144
	global_store_dwordx4 v15, v[156:159], s[4:5]
	v_fma_f32 v4, v156, s43, v108
	v_fma_f32 v5, v157, s43, v109
	v_fma_f32 v6, v158, s43, v110
	v_fma_f32 v7, v159, s43, v111
	v_add_u32_e32 v14, 0x2c00000, v144
	global_store_dwordx4 v14, v[4:7], s[4:5]
	v_fma_f32 v148, v4, s44, v112
	v_fma_f32 v149, v5, s44, v113
	v_fma_f32 v150, v6, s44, v114
	v_fma_f32 v151, v7, s44, v115
	v_add_u32_e32 v15, 0x2c80000, v144
	global_store_dwordx4 v15, v[148:151], s[4:5]
	v_fma_f32 v152, v148, s45, v116
	v_fma_f32 v153, v149, s45, v117
	v_fma_f32 v154, v150, s45, v118
	v_fma_f32 v155, v151, s45, v119
	v_add_u32_e32 v14, 0x2d00000, v144
	global_store_dwordx4 v14, v[152:155], s[4:5]
	v_fma_f32 v156, v152, s52, v120
	v_fma_f32 v157, v153, s52, v121
	v_fma_f32 v158, v154, s52, v122
	v_fma_f32 v159, v155, s52, v123
	v_add_u32_e32 v15, 0x2d80000, v144
	global_store_dwordx4 v15, v[156:159], s[4:5]
	v_fma_f32 v4, v156, s53, v124
	v_fma_f32 v5, v157, s53, v125
	v_fma_f32 v6, v158, s53, v126
	v_fma_f32 v7, v159, s53, v127
	v_add_u32_e32 v14, 0x2e00000, v144
	global_store_dwordx4 v14, v[4:7], s[4:5]
	v_fma_f32 v148, v4, s54, v128
	v_fma_f32 v149, v5, s54, v129
	v_fma_f32 v150, v6, s54, v130
	v_fma_f32 v151, v7, s54, v131
	v_add_u32_e32 v15, 0x2e80000, v144
	global_store_dwordx4 v15, v[148:151], s[4:5]
	v_fma_f32 v152, v148, s55, v132
	v_fma_f32 v153, v149, s55, v133
	v_fma_f32 v154, v150, s55, v134
	v_fma_f32 v155, v151, s55, v135
	v_add_u32_e32 v14, 0x2f00000, v144
	global_store_dwordx4 v14, v[152:155], s[4:5]
	v_fma_f32 v156, v152, s56, v136
	v_fma_f32 v157, v153, s56, v137
	v_fma_f32 v158, v154, s56, v138
	v_fma_f32 v159, v155, s56, v139
	v_add_u32_e32 v15, 0x2f80000, v144
	global_store_dwordx4 v15, v[156:159], s[4:5]
	v_fma_f32 v4, v156, s57, v140
	v_fma_f32 v5, v157, s57, v141
	v_fma_f32 v6, v158, s57, v142
	v_fma_f32 v7, v159, s57, v143
	s_waitcnt vmcnt(32)
; __device__ __forceinline__ void ssd_statepass(const Params& p, int task) {
;     ...
;   for (int c0 = 0; c0 < 128; c0 += 4) {
;     float4 v[4]; float d[4];
; #pragma unroll
;     for (int k = 0; k < 4; k++) { v[k] = *(const float4*)(base + (size_t)(c0 + k) * 131072); d[k] = cd[(c0 + k) * 16]; }
; #pragma unroll
;     for (int k = 0; k < 4; k++) {
;       *(float4*)(base + (size_t)(c0 + k) * 131072) = carry;
;       carry.x = carry.x * d[k] + v[k].x; carry.y = carry.y * d[k] + v[k].y;
;       carry.z = carry.z * d[k] + v[k].z; carry.w = carry.w * d[k] + v[k].w;
;     }
;   }
	v_add_u32_e32 v14, 0x3800000, v144
	global_load_dwordx4 v[80:83], v14, s[4:5]
	v_add_u32_e32 v15, 0x3880000, v144
	global_load_dwordx4 v[84:87], v15, s[4:5]
	v_add_u32_e32 v14, 0x3900000, v144
	global_load_dwordx4 v[88:91], v14, s[4:5]
	v_add_u32_e32 v15, 0x3980000, v144
	global_load_dwordx4 v[92:95], v15, s[4:5]
	v_add_u32_e32 v14, 0x3a00000, v144
	global_load_dwordx4 v[96:99], v14, s[4:5]
	v_add_u32_e32 v15, 0x3a80000, v144
	global_load_dwordx4 v[100:103], v15, s[4:5]
	v_add_u32_e32 v14, 0x3b00000, v144
	global_load_dwordx4 v[104:107], v14, s[4:5]
	v_add_u32_e32 v15, 0x3b80000, v144
	global_load_dwordx4 v[108:111], v15, s[4:5]
	v_add_u32_e32 v14, 0x3c00000, v144
	global_load_dwordx4 v[112:115], v14, s[4:5]
	v_add_u32_e32 v15, 0x3c80000, v144
	global_load_dwordx4 v[116:119], v15, s[4:5]
	v_add_u32_e32 v14, 0x3d00000, v144
	global_load_dwordx4 v[120:123], v14, s[4:5]
	v_add_u32_e32 v15, 0x3d80000, v144
	global_load_dwordx4 v[124:127], v15, s[4:5]
	v_add_u32_e32 v14, 0x3e00000, v144
	global_load_dwordx4 v[128:131], v14, s[4:5]
	v_add_u32_e32 v15, 0x3e80000, v144
	global_load_dwordx4 v[132:135], v15, s[4:5]
	v_add_u32_e32 v14, 0x3f00000, v144
	global_load_dwordx4 v[136:139], v14, s[4:5]
	v_add_u32_e32 v15, 0x3f80000, v144
	global_load_dwordx4 v[140:143], v15, s[4:5]
	s_waitcnt vmcnt(32)
	v_readlane_b32 s36, v9, 32
	v_readlane_b32 s37, v9, 33
	v_readlane_b32 s38, v9, 34
	v_readlane_b32 s39, v9, 35
	v_readlane_b32 s40, v9, 36
	v_readlane_b32 s41, v9, 37
	v_readlane_b32 s42, v9, 38
	v_readlane_b32 s43, v9, 39
	v_readlane_b32 s44, v9, 40
	v_readlane_b32 s45, v9, 41
	v_readlane_b32 s52, v9, 42
	v_readlane_b32 s53, v9, 43
	v_readlane_b32 s54, v9, 44
	v_readlane_b32 s55, v9, 45
	v_readlane_b32 s56, v9, 46
	v_readlane_b32 s57, v9, 47
	v_add_u32_e32 v14, 0x3000000, v144
	global_store_dwordx4 v14, v[4:7], s[4:5]
	v_fma_f32 v148, v4, s36, v16
	v_fma_f32 v149, v5, s36, v17
	v_fma_f32 v150, v6, s36, v18
	v_fma_f32 v151, v7, s36, v19
	v_add_u32_e32 v15, 0x3080000, v144
	global_store_dwordx4 v15, v[148:151], s[4:5]
	v_fma_f32 v152, v148, s37, v20
	v_fma_f32 v153, v149, s37, v21
	v_fma_f32 v154, v150, s37, v22
	v_fma_f32 v155, v151, s37, v23
	v_add_u32_e32 v14, 0x3100000, v144
	global_store_dwordx4 v14, v[152:155], s[4:5]
	v_fma_f32 v156, v152, s38, v24
	v_fma_f32 v157, v153, s38, v25
	v_fma_f32 v158, v154, s38, v26
	v_fma_f32 v159, v155, s38, v27
	v_add_u32_e32 v15, 0x3180000, v144
	global_store_dwordx4 v15, v[156:159], s[4:5]
	v_fma_f32 v4, v156, s39, v28
	v_fma_f32 v5, v157, s39, v29
	v_fma_f32 v6, v158, s39, v30
	v_fma_f32 v7, v159, s39, v31
	v_add_u32_e32 v14, 0x3200000, v144
	global_store_dwordx4 v14, v[4:7], s[4:5]
	v_fma_f32 v148, v4, s40, v32
	v_fma_f32 v149, v5, s40, v33
	v_fma_f32 v150, v6, s40, v34
	v_fma_f32 v151, v7, s40, v35
	v_add_u32_e32 v15, 0x3280000, v144
	global_store_dwordx4 v15, v[148:151], s[4:5]
	v_fma_f32 v152, v148, s41, v36
	v_fma_f32 v153, v149, s41, v37
	v_fma_f32 v154, v150, s41, v38
	v_fma_f32 v155, v151, s41, v39
	v_add_u32_e32 v14, 0x3300000, v144
	global_store_dwordx4 v14, v[152:155], s[4:5]
	v_fma_f32 v156, v152, s42, v40
	v_fma_f32 v157, v153, s42, v41
	v_fma_f32 v158, v154, s42, v42
	v_fma_f32 v159, v155, s42, v43
	v_add_u32_e32 v15, 0x3380000, v144
	global_store_dwordx4 v15, v[156:159], s[4:5]
	v_fma_f32 v4, v156, s43, v44
	v_fma_f32 v5, v157, s43, v45
	v_fma_f32 v6, v158, s43, v46
	v_fma_f32 v7, v159, s43, v47
	v_add_u32_e32 v14, 0x3400000, v144
	global_store_dwordx4 v14, v[4:7], s[4:5]
	v_fma_f32 v148, v4, s44, v48
	v_fma_f32 v149, v5, s44, v49
	v_fma_f32 v150, v6, s44, v50
	v_fma_f32 v151, v7, s44, v51
	v_add_u32_e32 v15, 0x3480000, v144
	global_store_dwordx4 v15, v[148:151], s[4:5]
	v_fma_f32 v152, v148, s45, v52
	v_fma_f32 v153, v149, s45, v53
	v_fma_f32 v154, v150, s45, v54
	v_fma_f32 v155, v151, s45, v55
	v_add_u32_e32 v14, 0x3500000, v144
	global_store_dwordx4 v14, v[152:155], s[4:5]
	v_fma_f32 v156, v152, s52, v56
	v_fma_f32 v157, v153, s52, v57
	v_fma_f32 v158, v154, s52, v58
	v_fma_f32 v159, v155, s52, v59
	v_add_u32_e32 v15, 0x3580000, v144
	global_store_dwordx4 v15, v[156:159], s[4:5]
	v_fma_f32 v4, v156, s53, v60
	v_fma_f32 v5, v157, s53, v61
	v_fma_f32 v6, v158, s53, v62
	v_fma_f32 v7, v159, s53, v63
	v_add_u32_e32 v14, 0x3600000, v144
	global_store_dwordx4 v14, v[4:7], s[4:5]
	v_fma_f32 v148, v4, s54, v64
	v_fma_f32 v149, v5, s54, v65
	v_fma_f32 v150, v6, s54, v66
	v_fma_f32 v151, v7, s54, v67
	v_add_u32_e32 v15, 0x3680000, v144
	global_store_dwordx4 v15, v[148:151], s[4:5]
	v_fma_f32 v152, v148, s55, v68
	v_fma_f32 v153, v149, s55, v69
	v_fma_f32 v154, v150, s55, v70
	v_fma_f32 v155, v151, s55, v71
	v_add_u32_e32 v14, 0x3700000, v144
	global_store_dwordx4 v14, v[152:155], s[4:5]
	v_fma_f32 v156, v152, s56, v72
	v_fma_f32 v157, v153, s56, v73
	v_fma_f32 v158, v154, s56, v74
	v_fma_f32 v159, v155, s56, v75
	v_add_u32_e32 v15, 0x3780000, v144
	global_store_dwordx4 v15, v[156:159], s[4:5]
	v_fma_f32 v4, v156, s57, v76
	v_fma_f32 v5, v157, s57, v77
	v_fma_f32 v6, v158, s57, v78
	v_fma_f32 v7, v159, s57, v79
	s_waitcnt vmcnt(16)
; __device__ __forceinline__ void ssd_statepass(const Params& p, int task) {
;     ...
; #pragma unroll
;     for (int k = 0; k < 4; k++) {
;       *(float4*)(base + (size_t)(c0 + k) * 131072) = carry;
;       carry.x = carry.x * d[k] + v[k].x; carry.y = carry.y * d[k] + v[k].y;
;       carry.z = carry.z * d[k] + v[k].z; carry.w = carry.w * d[k] + v[k].w;
;     }
	v_readlane_b32 s36, v9, 48
	v_readlane_b32 s37, v9, 49
	v_readlane_b32 s38, v9, 50
	v_readlane_b32 s39, v9, 51
	v_readlane_b32 s40, v9, 52
	v_readlane_b32 s41, v9, 53
	v_readlane_b32 s42, v9, 54
	v_readlane_b32 s43, v9, 55
	v_readlane_b32 s44, v9, 56
	v_readlane_b32 s45, v9, 57
	v_readlane_b32 s52, v9, 58
	v_readlane_b32 s53, v9, 59
	v_readlane_b32 s54, v9, 60
	v_readlane_b32 s55, v9, 61
	v_readlane_b32 s56, v9, 62
	v_readlane_b32 s57, v9, 63
	v_add_u32_e32 v14, 0x3800000, v144
	global_store_dwordx4 v14, v[4:7], s[4:5]
	v_fma_f32 v148, v4, s36, v80
	v_fma_f32 v149, v5, s36, v81
	v_fma_f32 v150, v6, s36, v82
	v_fma_f32 v151, v7, s36, v83
	v_add_u32_e32 v15, 0x3880000, v144
	global_store_dwordx4 v15, v[148:151], s[4:5]
	v_fma_f32 v152, v148, s37, v84
	v_fma_f32 v153, v149, s37, v85
	v_fma_f32 v154, v150, s37, v86
	v_fma_f32 v155, v151, s37, v87
	v_add_u32_e32 v14, 0x3900000, v144
	global_store_dwordx4 v14, v[152:155], s[4:5]
	v_fma_f32 v156, v152, s38, v88
	v_fma_f32 v157, v153, s38, v89
	v_fma_f32 v158, v154, s38, v90
	v_fma_f32 v159, v155, s38, v91
	v_add_u32_e32 v15, 0x3980000, v144
	global_store_dwordx4 v15, v[156:159], s[4:5]
	v_fma_f32 v4, v156, s39, v92
	v_fma_f32 v5, v157, s39, v93
	v_fma_f32 v6, v158, s39, v94
	v_fma_f32 v7, v159, s39, v95
	v_add_u32_e32 v14, 0x3a00000, v144
	global_store_dwordx4 v14, v[4:7], s[4:5]
	v_fma_f32 v148, v4, s40, v96
	v_fma_f32 v149, v5, s40, v97
	v_fma_f32 v150, v6, s40, v98
	v_fma_f32 v151, v7, s40, v99
	v_add_u32_e32 v15, 0x3a80000, v144
	global_store_dwordx4 v15, v[148:151], s[4:5]
	v_fma_f32 v152, v148, s41, v100
	v_fma_f32 v153, v149, s41, v101
	v_fma_f32 v154, v150, s41, v102
	v_fma_f32 v155, v151, s41, v103
	v_add_u32_e32 v14, 0x3b00000, v144
	global_store_dwordx4 v14, v[152:155], s[4:5]
	v_fma_f32 v156, v152, s42, v104
	v_fma_f32 v157, v153, s42, v105
	v_fma_f32 v158, v154, s42, v106
	v_fma_f32 v159, v155, s42, v107
	v_add_u32_e32 v15, 0x3b80000, v144
	global_store_dwordx4 v15, v[156:159], s[4:5]
	v_fma_f32 v4, v156, s43, v108
	v_fma_f32 v5, v157, s43, v109
	v_fma_f32 v6, v158, s43, v110
	v_fma_f32 v7, v159, s43, v111
	v_add_u32_e32 v14, 0x3c00000, v144
	global_store_dwordx4 v14, v[4:7], s[4:5]
	v_fma_f32 v148, v4, s44, v112
	v_fma_f32 v149, v5, s44, v113
	v_fma_f32 v150, v6, s44, v114
	v_fma_f32 v151, v7, s44, v115
	v_add_u32_e32 v15, 0x3c80000, v144
	global_store_dwordx4 v15, v[148:151], s[4:5]
	v_fma_f32 v152, v148, s45, v116
	v_fma_f32 v153, v149, s45, v117
	v_fma_f32 v154, v150, s45, v118
	v_fma_f32 v155, v151, s45, v119
	v_add_u32_e32 v14, 0x3d00000, v144
	global_store_dwordx4 v14, v[152:155], s[4:5]
	v_fma_f32 v156, v152, s52, v120
	v_fma_f32 v157, v153, s52, v121
	v_fma_f32 v158, v154, s52, v122
	v_fma_f32 v159, v155, s52, v123
	v_add_u32_e32 v15, 0x3d80000, v144
	global_store_dwordx4 v15, v[156:159], s[4:5]
	v_fma_f32 v4, v156, s53, v124
	v_fma_f32 v5, v157, s53, v125
	v_fma_f32 v6, v158, s53, v126
	v_fma_f32 v7, v159, s53, v127
	v_add_u32_e32 v14, 0x3e00000, v144
	global_store_dwordx4 v14, v[4:7], s[4:5]
	v_fma_f32 v148, v4, s54, v128
	v_fma_f32 v149, v5, s54, v129
	v_fma_f32 v150, v6, s54, v130
	v_fma_f32 v151, v7, s54, v131
	v_add_u32_e32 v15, 0x3e80000, v144
	global_store_dwordx4 v15, v[148:151], s[4:5]
	v_fma_f32 v152, v148, s55, v132
	v_fma_f32 v153, v149, s55, v133
	v_fma_f32 v154, v150, s55, v134
	v_fma_f32 v155, v151, s55, v135
	v_add_u32_e32 v14, 0x3f00000, v144
	global_store_dwordx4 v14, v[152:155], s[4:5]
	v_fma_f32 v156, v152, s56, v136
	v_fma_f32 v157, v153, s56, v137
	v_fma_f32 v158, v154, s56, v138
	v_fma_f32 v159, v155, s56, v139
	v_add_u32_e32 v15, 0x3f80000, v144
	global_store_dwordx4 v15, v[156:159], s[4:5]
	v_fma_f32 v4, v156, s57, v140
	v_fma_f32 v5, v157, s57, v141
	v_fma_f32 v6, v158, s57, v142
	v_fma_f32 v7, v159, s57, v143
	s_waitcnt vmcnt(0)
